# S5B up-front loads + static s_setprio 1 for waves 4-7 at each phase start
# baseline (speedup 1.0000x reference)
_Z4mega6Paramsii:
	v_readfirstlane_b32 s100, v0
	s_and_b32 s100, s100, 0x300
	s_add_u32 s4, s0, 0x528
	s_addc_u32 s5, s1, 0
	v_and_b32_e32 v163, 0x3ff, v0
	v_writelane_b32 v251, s4, 0
	s_nop 1
	v_writelane_b32 v251, s5, 1
	v_writelane_b32 v251, s0, 2
	s_load_dwordx2 s[8:9], s[0:1], 0x528
	s_nop 0
	v_writelane_b32 v251, s1, 3
	v_writelane_b32 v251, s2, 4
	s_nop 0
	v_writelane_b32 v251, s2, 5
	v_cmp_eq_u32_e64 s[2:3], 0, v163
	s_mov_b64 s[0:1], exec
	s_nop 0
	v_writelane_b32 v251, s2, 6
	s_nop 1
	v_writelane_b32 v251, s3, 7
	s_and_b64 s[2:3], s[0:1], s[2:3]
	s_mov_b64 exec, s[2:3]
	s_cbranch_execz .LBB0_2
	v_mov_b32_e32 v1, 0
	v_mov_b32_e32 v2, 0x24400
	ds_write_b32 v2, v1
	v_mov_b32_e32 v2, 0x24404
	ds_write_b32 v2, v1

.LBB0_8:
	s_cmp_eq_u32 s100, 0
	s_cbranch_scc1 .Lprio_skip
	s_setprio 1

	.amdhsa_kernel _Z4mega6Paramsii
		.amdhsa_group_segment_fixed_size 148496
		.amdhsa_private_segment_fixed_size 0
		.amdhsa_kernarg_size 1576
		.amdhsa_user_sgpr_count 2
		.amdhsa_user_sgpr_dispatch_ptr 0
		.amdhsa_user_sgpr_queue_ptr 0
		.amdhsa_user_sgpr_kernarg_segment_ptr 1
		.amdhsa_user_sgpr_dispatch_id 0
		.amdhsa_user_sgpr_kernarg_preload_length 0
		.amdhsa_user_sgpr_kernarg_preload_offset 0
		.amdhsa_user_sgpr_private_segment_size 0
		.amdhsa_uses_dynamic_stack 0
		.amdhsa_enable_private_segment 0
		.amdhsa_system_sgpr_workgroup_id_x 1
		.amdhsa_system_sgpr_workgroup_id_y 0
		.amdhsa_system_sgpr_workgroup_id_z 0
		.amdhsa_system_sgpr_workgroup_info 0
		.amdhsa_system_vgpr_workitem_id 2
		.amdhsa_next_free_vgpr 256
		.amdhsa_next_free_sgpr 102
		.amdhsa_accum_offset 256
		.amdhsa_reserve_vcc 1
		.amdhsa_float_round_mode_32 0
		.amdhsa_float_round_mode_16_64 0
		.amdhsa_float_denorm_mode_32 3
		.amdhsa_float_denorm_mode_16_64 3
		.amdhsa_dx10_clamp 1
		.amdhsa_ieee_mode 1
		.amdhsa_fp16_overflow 0
		.amdhsa_tg_split 0
		.amdhsa_exception_fp_ieee_invalid_op 0
		.amdhsa_exception_fp_denorm_src 0
		.amdhsa_exception_fp_ieee_div_zero 0
		.amdhsa_exception_fp_ieee_overflow 0
		.amdhsa_exception_fp_ieee_underflow 0
		.amdhsa_exception_fp_ieee_inexact 0
		.amdhsa_exception_int_div_zero 0
	.end_amdhsa_kernel

amdhsa.kernels:
  - .agpr_count:     0
    .args:
      - .offset:         0
        .size:           1312
        .value_kind:     by_value
      - .offset:         1312
        .size:           4
        .value_kind:     by_value
      - .offset:         1316
        .size:           4
        .value_kind:     by_value
      - .offset:         1320
        .size:           4
        .value_kind:     hidden_block_count_x
      - .offset:         1324
        .size:           4
        .value_kind:     hidden_block_count_y
      - .offset:         1328
        .size:           4
        .value_kind:     hidden_block_count_z
      - .offset:         1332
        .size:           2
        .value_kind:     hidden_group_size_x
      - .offset:         1334
        .size:           2
        .value_kind:     hidden_group_size_y
      - .offset:         1336
        .size:           2
        .value_kind:     hidden_group_size_z
      - .offset:         1338
        .size:           2
        .value_kind:     hidden_remainder_x
      - .offset:         1340
        .size:           2
        .value_kind:     hidden_remainder_y
      - .offset:         1342
        .size:           2
        .value_kind:     hidden_remainder_z
      - .offset:         1360
        .size:           8
        .value_kind:     hidden_global_offset_x
      - .offset:         1368
        .size:           8
        .value_kind:     hidden_global_offset_y
      - .offset:         1376
        .size:           8
        .value_kind:     hidden_global_offset_z
      - .offset:         1384
        .size:           2
        .value_kind:     hidden_grid_dims
      - .offset:         1408
        .size:           8
        .value_kind:     hidden_multigrid_sync_arg
    .group_segment_fixed_size: 148496
    .kernarg_segment_align: 8
    .kernarg_segment_size: 1576
    .language:       OpenCL C
    .language_version:
      - 2
      - 0
    .max_flat_workgroup_size: 512
    .name:           _Z4mega6Paramsii
    .private_segment_fixed_size: 0
    .sgpr_count:     108
    .sgpr_spill_count: 557
    .symbol:         _Z4mega6Paramsii.kd
    .uniform_work_group_size: 1
    .uses_dynamic_stack: false
    .vgpr_count:     256
    .vgpr_spill_count: 0
    .wavefront_size: 64
